# sample ffn-down task: K loop unrolled with 11 steps of operand loads in flight instead of load-wait-MFMA per step
# speedup vs baseline: 1.0191x; 1.0037x over previous
; DEV unsigned pk2(float lo, float hi) { return (unsigned)f2bf(lo) | ((unsigned)f2bf(hi) << 16); }
; DEV int crow(int r, int hi) { return (r & 3) + 8 * (r >> 2) + 4 * hi; }
; template <bool F32A, bool PAIR, class Epi> DEV void sgemm_wg(const void* Aptr, int lda, const bf16_t* Bt, int ldb, int K, int n0, int n1, int wave, int lane, LAS float* red, Epi epi) {
;     ...
;     for (int k = kb; k < kb + kper; k += 16) {
;         bf16x8 a;
;         if (F32A) { const float* ap = (const float*)Aptr + (size_t)r32 * lda + k + 8 * hi; const f32x4 x0 = *(const f32x4*)ap, x1 = *(const f32x4*)(ap + 4);
;             ss += (x0.x * x0.x + x0.y * x0.y) + (x0.z * x0.z + x0.w * x0.w) + (x1.x * x1.x + x1.y * x1.y) + (x1.z * x1.z + x1.w * x1.w);
;             u32x4 w; w.x = pk2(x0.x, x0.y); w.y = pk2(x0.z, x0.w); w.z = pk2(x1.x, x1.y); w.w = pk2(x1.z, x1.w); a = __builtin_bit_cast(bf16x8, w); }
;         else a = *(const bf16x8*)((const bf16_t*)Aptr + (size_t)r32 * lda + k + 8 * hi);
;         acc0 = __builtin_amdgcn_mfma_f32_32x32x16_bf16(a, *(const bf16x8*)(bp0 + k), acc0, 0, 0, 0);
;         if (PAIR) acc1 = __builtin_amdgcn_mfma_f32_32x32x16_bf16(a, *(const bf16x8*)(bp1 + k), acc1, 0, 0, 0);
;     }
;     LAS float* ssw = red + 2 * 8 * 1024;
; #pragma unroll
;     for (int r = 0; r < 16; ++r) { red[(wave * 16 + r) * 64 + lane] = acc0[r]; if (PAIR) red[8 * 1024 + (wave * 16 + r) * 64 + lane] = acc1[r]; }
;     if (F32A) { ss += shfl_xor_(ss, 32); if (lane < 32) ssw[wave * 32 + lane] = ss; }
;     __syncthreads();
; #pragma unroll
;     for (int i = 0; i < 2; ++i) { const int e = wave * 64 + lane + 512 * i, r = e >> 6, ln = e & 63, row = crow(r, ln >> 5);
;         float v0 = 0.f, v1 = 0.f, sq = 0.f;
; #pragma unroll
;         for (int w = 0; w < 8; ++w) { v0 += red[(w * 16 + r) * 64 + ln]; if (PAIR) v1 += red[8 * 1024 + (w * 16 + r) * 64 + ln]; if (F32A) sq += ssw[w * 32 + row]; }
;         epi(row, ln & 31, v0, v1, sq); }
; __global__ void __launch_bounds__(512, 2) mk_fwd(MKArgs args) {
;     ...
;               for (int k = k0_; k >= 0 && k < DM / 32; k += G) {
;                 sgemm_wg<false, false>(ws + WS_HS, DFF, (const bf16_t*)(wl + WL_FFO), DFF, DFF, 32 * k, 0, wave, lane, (LAS float*)(ldsl + RING_OFF), [&](int row, int c, float v, float, float) { xs[(size_t)row * DM + 32 * k + c] += v; });
;                 if (rd) wg_post(ctl + CW_S6 + 64 * l, wave_s); } }
.LBB0_2317:
	global_load_dwordx4 v[42:45], v[30:31], off
	global_load_dwordx4 v[46:49], v[28:29], off
	global_load_dwordx4 v[50:53], v[30:31], off offset:32
	global_load_dwordx4 v[54:57], v[28:29], off offset:32
	global_load_dwordx4 v[58:61], v[30:31], off offset:64
	global_load_dwordx4 v[62:65], v[28:29], off offset:64
	global_load_dwordx4 v[66:69], v[30:31], off offset:96
	global_load_dwordx4 v[70:73], v[28:29], off offset:96
	global_load_dwordx4 v[74:77], v[30:31], off offset:128
	global_load_dwordx4 v[78:81], v[28:29], off offset:128
	global_load_dwordx4 v[82:85], v[30:31], off offset:160
	global_load_dwordx4 v[86:89], v[28:29], off offset:160
	global_load_dwordx4 v[90:93], v[30:31], off offset:192
	global_load_dwordx4 v[94:97], v[28:29], off offset:192
	global_load_dwordx4 v[98:101], v[30:31], off offset:224
	global_load_dwordx4 v[102:105], v[28:29], off offset:224
	global_load_dwordx4 v[106:109], v[30:31], off offset:256
	global_load_dwordx4 v[110:113], v[28:29], off offset:256
	global_load_dwordx4 v[114:117], v[30:31], off offset:288
	global_load_dwordx4 v[118:121], v[28:29], off offset:288
	global_load_dwordx4 v[122:125], v[30:31], off offset:320
	global_load_dwordx4 v[126:129], v[28:29], off offset:320
	s_waitcnt vmcnt(20)
	v_mfma_f32_32x32x16_bf16 v[2:17], v[42:45], v[46:49], v[2:17]
	global_load_dwordx4 v[42:45], v[30:31], off offset:352
	global_load_dwordx4 v[46:49], v[28:29], off offset:352
	s_waitcnt vmcnt(20)
	v_mfma_f32_32x32x16_bf16 v[2:17], v[50:53], v[54:57], v[2:17]
	global_load_dwordx4 v[50:53], v[30:31], off offset:384
	global_load_dwordx4 v[54:57], v[28:29], off offset:384
	s_waitcnt vmcnt(20)
	v_mfma_f32_32x32x16_bf16 v[2:17], v[58:61], v[62:65], v[2:17]
	global_load_dwordx4 v[58:61], v[30:31], off offset:416
	global_load_dwordx4 v[62:65], v[28:29], off offset:416
	s_waitcnt vmcnt(20)
	v_mfma_f32_32x32x16_bf16 v[2:17], v[66:69], v[70:73], v[2:17]
	global_load_dwordx4 v[66:69], v[30:31], off offset:448
	global_load_dwordx4 v[70:73], v[28:29], off offset:448
	s_waitcnt vmcnt(20)
	v_mfma_f32_32x32x16_bf16 v[2:17], v[74:77], v[78:81], v[2:17]
	global_load_dwordx4 v[74:77], v[30:31], off offset:480
	global_load_dwordx4 v[78:81], v[28:29], off offset:480
	s_waitcnt vmcnt(20)
	v_mfma_f32_32x32x16_bf16 v[2:17], v[82:85], v[86:89], v[2:17]
	global_load_dwordx4 v[82:85], v[30:31], off offset:512
	global_load_dwordx4 v[86:89], v[28:29], off offset:512
	s_waitcnt vmcnt(20)
	v_mfma_f32_32x32x16_bf16 v[2:17], v[90:93], v[94:97], v[2:17]
	global_load_dwordx4 v[90:93], v[30:31], off offset:544
	global_load_dwordx4 v[94:97], v[28:29], off offset:544
	s_waitcnt vmcnt(20)
	v_mfma_f32_32x32x16_bf16 v[2:17], v[98:101], v[102:105], v[2:17]
	global_load_dwordx4 v[98:101], v[30:31], off offset:576
	global_load_dwordx4 v[102:105], v[28:29], off offset:576
	s_waitcnt vmcnt(20)
	v_mfma_f32_32x32x16_bf16 v[2:17], v[106:109], v[110:113], v[2:17]
	global_load_dwordx4 v[106:109], v[30:31], off offset:608
	global_load_dwordx4 v[110:113], v[28:29], off offset:608
	s_waitcnt vmcnt(20)
	v_mfma_f32_32x32x16_bf16 v[2:17], v[114:117], v[118:121], v[2:17]
	global_load_dwordx4 v[114:117], v[30:31], off offset:640
	global_load_dwordx4 v[118:121], v[28:29], off offset:640
	s_waitcnt vmcnt(20)
	v_mfma_f32_32x32x16_bf16 v[2:17], v[122:125], v[126:129], v[2:17]
	global_load_dwordx4 v[122:125], v[30:31], off offset:672
	global_load_dwordx4 v[126:129], v[28:29], off offset:672
	s_waitcnt vmcnt(20)
	v_mfma_f32_32x32x16_bf16 v[2:17], v[42:45], v[46:49], v[2:17]
	s_waitcnt vmcnt(18)
	v_mfma_f32_32x32x16_bf16 v[2:17], v[50:53], v[54:57], v[2:17]
	s_waitcnt vmcnt(16)
	v_mfma_f32_32x32x16_bf16 v[2:17], v[58:61], v[62:65], v[2:17]
	s_waitcnt vmcnt(14)
	v_mfma_f32_32x32x16_bf16 v[2:17], v[66:69], v[70:73], v[2:17]
	s_waitcnt vmcnt(12)
	v_mfma_f32_32x32x16_bf16 v[2:17], v[74:77], v[78:81], v[2:17]
	s_waitcnt vmcnt(10)
	v_mfma_f32_32x32x16_bf16 v[2:17], v[82:85], v[86:89], v[2:17]
	s_waitcnt vmcnt(8)
	v_mfma_f32_32x32x16_bf16 v[2:17], v[90:93], v[94:97], v[2:17]
	s_waitcnt vmcnt(6)
	v_mfma_f32_32x32x16_bf16 v[2:17], v[98:101], v[102:105], v[2:17]
	s_waitcnt vmcnt(4)
	v_mfma_f32_32x32x16_bf16 v[2:17], v[106:109], v[110:113], v[2:17]
	s_waitcnt vmcnt(2)
	v_mfma_f32_32x32x16_bf16 v[2:17], v[114:117], v[118:121], v[2:17]
	s_waitcnt vmcnt(0)
	v_mfma_f32_32x32x16_bf16 v[2:17], v[122:125], v[126:129], v[2:17]
	v_add_u32_e32 v28, s10, v32
	s_nop 9
	ds_write2st64_b32 v28, v2, v3 offset1:1
	ds_write2st64_b32 v28, v4, v5 offset0:2 offset1:3
	ds_write2st64_b32 v28, v6, v7 offset0:4 offset1:5
	ds_write2st64_b32 v28, v8, v9 offset0:6 offset1:7
	ds_write2st64_b32 v28, v10, v11 offset0:8 offset1:9
	ds_write2st64_b32 v28, v12, v13 offset0:10 offset1:11
	ds_write2st64_b32 v28, v14, v15 offset0:12 offset1:13
	ds_write2st64_b32 v28, v16, v17 offset0:14 offset1:15
	s_waitcnt lgkmcnt(0)
	s_barrier
	ds_read2st64_b32 v[4:5], v33 offset1:8
	ds_read2st64_b32 v[6:7], v33 offset0:16 offset1:24
	s_lshl_b32 s56, s8, 5
	v_lshl_add_u64 v[2:3], s[56:57], 2, v[18:19]
	v_lshl_add_u64 v[30:31], v[2:3], 0, v[20:21]
	s_waitcnt lgkmcnt(1)
	v_add_f32_e32 v4, 0, v4
	s_waitcnt lgkmcnt(0)
	v_add_f32_e32 v4, v4, v6
	global_load_dword v6, v[30:31], off
	ds_read2st64_b32 v[8:9], v33 offset0:32 offset1:40
	ds_read2st64_b32 v[10:11], v33 offset0:48 offset1:56
	ds_read2st64_b32 v[12:13], v33 offset0:64 offset1:72
	ds_read2st64_b32 v[14:15], v33 offset0:80 offset1:88
	ds_read2st64_b32 v[16:17], v33 offset0:96 offset1:104
	s_waitcnt lgkmcnt(4)
	v_add_f32_e32 v4, v4, v8
	ds_read2st64_b32 v[28:29], v33 offset0:112 offset1:120
	s_waitcnt lgkmcnt(4)
	v_add_f32_e32 v4, v4, v10
	s_waitcnt lgkmcnt(3)
	v_add_f32_e32 v4, v4, v12
	s_waitcnt lgkmcnt(2)
	v_add_f32_e32 v4, v4, v14
	s_waitcnt lgkmcnt(1)
	v_add_f32_e32 v4, v4, v16
	s_waitcnt lgkmcnt(0)
	v_add_f32_e32 v4, v4, v28
	v_lshl_add_u64 v[2:3], v[2:3], 0, v[22:23]
	s_andn2_b64 vcc, exec, s[0:1]
	s_waitcnt vmcnt(0)
	v_add_f32_e32 v4, v4, v6
	global_store_dword v[30:31], v4, off
	v_add_f32_e32 v4, 0, v5
	global_load_dword v5, v[2:3], off
	v_add_f32_e32 v4, v4, v7
	v_add_f32_e32 v4, v4, v9
	v_add_f32_e32 v4, v4, v11
	v_add_f32_e32 v4, v4, v13
	v_add_f32_e32 v4, v4, v15
	v_add_f32_e32 v4, v4, v17
	v_add_f32_e32 v4, v4, v29
	s_waitcnt vmcnt(0)
	v_add_f32_e32 v4, v4, v5
	global_store_dword v[2:3], v4, off
	s_cbranch_vccnz .LBB0_2315
	v_readlane_b32 s4, v254, 40
	v_readlane_b32 s5, v254, 41
	s_and_b64 vcc, exec, s[4:5]
	s_barrier
	s_cbranch_vccnz .LBB0_2315
	v_mbcnt_lo_u32_b32 v2, -1, 0
	v_mbcnt_hi_u32_b32 v2, -1, v2
	s_nop 0
	v_cmp_eq_u32_e32 vcc, 0, v2
	s_and_saveexec_b64 s[4:5], vcc
	s_cbranch_execz .LBB0_2314
	s_mov_b64 s[6:7], exec
	v_mbcnt_lo_u32_b32 v2, s6, 0
	buffer_wbl2 sc1
	s_waitcnt vmcnt(0)
	s_waitcnt vmcnt(0)
	v_mbcnt_hi_u32_b32 v2, s7, v2
	v_cmp_eq_u32_e32 vcc, 0, v2
	s_and_b64 s[12:13], exec, vcc
	s_mov_b64 exec, s[12:13]
	s_cbranch_execz .LBB0_2314
	s_bcnt1_i32_b64 s6, s[6:7]
	v_mov_b32_e32 v2, s6
	global_atomic_add v1, v2, s[2:3]
	s_branch .LBB0_2314
